# pack/row-sum block at step head; first V fragment reads issued at step head, second group after the S MFMAs
# baseline (speedup 1.0000x reference)
.LBB0_280:
	s_waitcnt lgkmcnt(9)
	v_mfma_f32_32x32x16_bf16 v[66:81], v[166:169], v[134:137], v[66:81]
	s_waitcnt lgkmcnt(8)
	v_mfma_f32_32x32x16_bf16 v[82:97], v[162:165], v[134:137], v[82:97]
	s_waitcnt lgkmcnt(7)
	v_mfma_f32_32x32x16_bf16 v[66:81], v[158:161], v[138:141], v[66:81]
	s_waitcnt lgkmcnt(6)
	v_mfma_f32_32x32x16_bf16 v[82:97], v[154:157], v[138:141], v[82:97]
	s_waitcnt lgkmcnt(5)
	v_mfma_f32_32x32x16_bf16 v[66:81], v[150:153], v[142:145], v[66:81]
	s_waitcnt lgkmcnt(4)
	v_mfma_f32_32x32x16_bf16 v[82:97], v[146:149], v[142:145], v[82:97]
	ds_read_b128 v[150:153], v209 offset:53248
	ds_read_b128 v[146:149], v209 offset:49152
	ds_read_b128 v[154:157], v209 offset:57344
	ds_read_b128 v[158:161], v209 offset:61440
	s_and_b32 s0, s77, 0x3f0000
	s_lshl_b32 s22, s0, 1
	s_mov_b32 m0, s73
	v_lshl_add_u64 v[164:165], v[188:189], 0, s[22:23]
	global_load_lds_dwordx4 v[164:165], off
	v_lshl_add_u64 v[164:165], v[192:193], 0, s[22:23]
	s_mov_b32 m0, s31
	s_lshl_b32 s22, s15, 1
	global_load_lds_dwordx4 v[164:165], off
	v_lshl_add_u64 v[164:165], v[190:191], 0, s[22:23]
	s_mov_b32 m0, s71
	global_load_lds_dwordx4 v[164:165], off
	v_lshl_add_u64 v[164:165], v[194:195], 0, s[22:23]
	s_mov_b32 m0, s72
	s_nop 0
	global_load_lds_dwordx4 v[164:165], off
	s_waitcnt lgkmcnt(4)
	v_mfma_f32_32x32x16_bf16 v[50:65], v[98:101], v[114:117], v[50:65]
	ds_read_b128 v[114:117], v210 offset:53248
	v_exp_f32_e32 v66, v66
	v_exp_f32_e32 v67, v67
	v_mfma_f32_32x32x16_bf16 v[34:49], v[98:101], v[118:121], v[34:49]
	ds_read_b128 v[118:121], v210 offset:57344
	v_exp_f32_e32 v68, v68
	v_exp_f32_e32 v69, v69
	v_mfma_f32_32x32x16_bf16 v[18:33], v[98:101], v[122:125], v[18:33]
	ds_read_b128 v[122:125], v210 offset:61440
	v_exp_f32_e32 v70, v70
	v_exp_f32_e32 v71, v71
	v_mfma_f32_32x32x16_bf16 v[2:17], v[98:101], v[126:129], v[2:17]
	ds_read_b128 v[98:101], v210 offset:49152
	v_exp_f32_e32 v72, v72
	v_exp_f32_e32 v73, v73
	s_waitcnt lgkmcnt(4)
	v_mfma_f32_32x32x16_bf16 v[50:65], v[102:105], v[146:149], v[50:65]
	ds_read_b128 v[126:129], v212 offset:53248
	v_exp_f32_e32 v74, v74
	v_exp_f32_e32 v75, v75
	v_mfma_f32_32x32x16_bf16 v[34:49], v[102:105], v[150:153], v[34:49]
	ds_read_b128 v[146:149], v212 offset:57344
	v_exp_f32_e32 v76, v76
	v_exp_f32_e32 v77, v77
	v_mfma_f32_32x32x16_bf16 v[18:33], v[102:105], v[154:157], v[18:33]
	ds_read_b128 v[150:153], v212 offset:61440
	v_exp_f32_e32 v78, v78
	v_exp_f32_e32 v79, v79
	v_mfma_f32_32x32x16_bf16 v[2:17], v[102:105], v[158:161], v[2:17]
	ds_read_b128 v[102:105], v212 offset:49152
	v_exp_f32_e32 v80, v80
	v_exp_f32_e32 v81, v81
	s_waitcnt lgkmcnt(0)
	v_mfma_f32_32x32x16_bf16 v[50:65], v[106:109], v[98:101], v[50:65]
	v_exp_f32_e32 v82, v82
	v_exp_f32_e32 v83, v83
	v_mfma_f32_32x32x16_bf16 v[34:49], v[106:109], v[114:117], v[34:49]
	v_exp_f32_e32 v84, v84
	v_exp_f32_e32 v85, v85
	v_mfma_f32_32x32x16_bf16 v[18:33], v[106:109], v[118:121], v[18:33]
	v_exp_f32_e32 v86, v86
	v_exp_f32_e32 v87, v87
	v_mfma_f32_32x32x16_bf16 v[2:17], v[106:109], v[122:125], v[2:17]
	v_exp_f32_e32 v88, v88
	v_exp_f32_e32 v89, v89
	v_mfma_f32_32x32x16_bf16 v[50:65], v[110:113], v[102:105], v[50:65]
	v_exp_f32_e32 v90, v90
	v_exp_f32_e32 v91, v91
	v_mfma_f32_32x32x16_bf16 v[34:49], v[110:113], v[126:129], v[34:49]
	v_exp_f32_e32 v92, v92
	v_exp_f32_e32 v93, v93
	v_mfma_f32_32x32x16_bf16 v[18:33], v[110:113], v[146:149], v[18:33]
	v_exp_f32_e32 v94, v94
	v_exp_f32_e32 v95, v95
	v_mfma_f32_32x32x16_bf16 v[2:17], v[110:113], v[150:153], v[2:17]
	v_exp_f32_e32 v96, v96
	v_exp_f32_e32 v97, v97
	s_waitcnt vmcnt(0)
	s_add_i32 s76, s76, 2
	s_add_i32 s77, s77, 0x20000
	s_cmp_gt_u32 s76, 61
	s_waitcnt vmcnt(0)
	s_barrier
	s_cbranch_scc1 .LBB0_295

.LBB0_284:
	ds_read_b128 v[174:177], v202 offset:16384
	ds_read_b128 v[170:173], v202 offset:24576
	ds_read_b128 v[166:169], v204 offset:16384
	ds_read_b128 v[162:165], v204 offset:24576
	ds_read_b128 v[158:161], v205 offset:16384
	ds_read_b128 v[154:157], v205 offset:24576
	ds_read_b128 v[150:153], v206 offset:16384
	ds_read_b128 v[146:149], v206 offset:24576
	v_pk_add_f32 v[98:99], v[66:67], v[82:83]
	v_pk_add_f32 v[100:101], v[68:69], v[84:85]
	v_pk_add_f32 v[102:103], v[70:71], v[86:87]
	v_pk_add_f32 v[104:105], v[72:73], v[88:89]
	v_pk_add_f32 v[106:107], v[74:75], v[90:91]
	v_pk_add_f32 v[108:109], v[76:77], v[92:93]
	v_pk_add_f32 v[110:111], v[78:79], v[94:95]
	v_pk_add_f32 v[112:113], v[80:81], v[96:97]
	v_pk_add_f32 v[98:99], v[98:99], v[100:101]
	v_pk_add_f32 v[102:103], v[102:103], v[104:105]
	v_pk_add_f32 v[106:107], v[106:107], v[108:109]
	v_pk_add_f32 v[110:111], v[110:111], v[112:113]
	v_pk_add_f32 v[98:99], v[98:99], v[102:103]
	v_pk_add_f32 v[106:107], v[106:107], v[110:111]
	v_cvt_pk_bf16_f32 v66, v66, v67
	v_cvt_pk_bf16_f32 v67, v68, v69
	v_cvt_pk_bf16_f32 v68, v70, v71
	v_cvt_pk_bf16_f32 v69, v72, v73
	v_pk_add_f32 v[98:99], v[98:99], v[106:107]
	v_cvt_pk_bf16_f32 v70, v74, v75
	v_cvt_pk_bf16_f32 v71, v76, v77
	v_cvt_pk_bf16_f32 v72, v78, v79
	v_cvt_pk_bf16_f32 v73, v80, v81
	v_cvt_pk_bf16_f32 v74, v82, v83
	v_cvt_pk_bf16_f32 v75, v84, v85
	v_cvt_pk_bf16_f32 v76, v86, v87
	v_cvt_pk_bf16_f32 v77, v88, v89
	v_cvt_pk_bf16_f32 v78, v90, v91
	v_cvt_pk_bf16_f32 v79, v92, v93
	v_cvt_pk_bf16_f32 v80, v94, v95
	v_cvt_pk_bf16_f32 v81, v96, v97
	v_add_f32_e32 v114, v98, v99
	s_nop 0
	v_add_f32_e32 v0, v114, v213
	ds_read_b128 v[82:85], v208 offset:32768
	ds_read_b128 v[86:89], v208 offset:36864
	ds_read_b128 v[90:93], v208 offset:40960
	ds_read_b128 v[94:97], v208 offset:45056
	s_add_i32 s0, s78, 64
	s_and_b32 s80, s0, 0xfc0
	s_or_b32 s0, s80, 63
	s_cmp_gt_i32 s0, s74
	s_cselect_b64 s[40:41], -1, 0
	s_cmp_lt_i32 s80, s75
	s_cselect_b64 s[0:1], -1, 0
	s_and_b64 s[14:15], s[40:41], s[0:1]
	s_andn2_b64 vcc, exec, s[14:15]
	s_mov_b64 s[14:15], -1
	s_cbranch_vccz .LBB0_286
	s_waitcnt lgkmcnt(11)
	v_mfma_f32_32x32x16_bf16 v[114:129], v[174:177], v[130:133], 0
	s_mov_b64 s[14:15], 0
	s_waitcnt lgkmcnt(10)
	v_mfma_f32_32x32x16_bf16 v[98:113], v[170:173], v[130:133], 0
.LBB0_286:
	s_andn2_b64 vcc, exec, s[14:15]
	s_cbranch_vccnz .LBB0_288
	v_lshl_add_u32 v112, s80, 2, v207
	s_nop 8
	v_add_u32_e32 v112, 0x500, v112
	ds_read2_b32 v[114:115], v112 offset0:0 offset1:1
	ds_read2_b32 v[98:99], v112 offset0:32 offset1:33
	ds_read2_b32 v[116:117], v112 offset0:2 offset1:3
	ds_read2_b32 v[100:101], v112 offset0:34 offset1:35
	ds_read2_b32 v[118:119], v112 offset0:4 offset1:5
	ds_read2_b32 v[102:103], v112 offset0:36 offset1:37
	ds_read2_b32 v[120:121], v112 offset0:6 offset1:7
	ds_read2_b32 v[104:105], v112 offset0:38 offset1:39
	ds_read2_b32 v[122:123], v112 offset0:16 offset1:17
	ds_read2_b32 v[124:125], v112 offset0:18 offset1:19
	ds_read2_b32 v[126:127], v112 offset0:20 offset1:21
	ds_read2_b32 v[128:129], v112 offset0:22 offset1:23
	ds_read2_b32 v[106:107], v112 offset0:48 offset1:49
	ds_read2_b32 v[108:109], v112 offset0:50 offset1:51
	ds_read2_b32 v[110:111], v112 offset0:52 offset1:53
	ds_read2_b32 v[112:113], v112 offset0:54 offset1:55
	s_waitcnt lgkmcnt(4)
	v_mfma_f32_32x32x16_bf16 v[114:129], v[174:177], v[130:133], v[114:129]
	s_waitcnt lgkmcnt(0)
	v_mfma_f32_32x32x16_bf16 v[98:113], v[170:173], v[130:133], v[98:113]
.LBB0_288:
	s_waitcnt lgkmcnt(9)
	v_mfma_f32_32x32x16_bf16 v[114:129], v[166:169], v[134:137], v[114:129]
	s_waitcnt lgkmcnt(8)
	v_mfma_f32_32x32x16_bf16 v[98:113], v[162:165], v[134:137], v[98:113]
	s_waitcnt lgkmcnt(7)
	v_mfma_f32_32x32x16_bf16 v[114:129], v[158:161], v[138:141], v[114:129]
	s_waitcnt lgkmcnt(6)
	v_mfma_f32_32x32x16_bf16 v[98:113], v[154:157], v[138:141], v[98:113]
	s_waitcnt lgkmcnt(5)
	v_mfma_f32_32x32x16_bf16 v[114:129], v[150:153], v[142:145], v[114:129]
	s_waitcnt lgkmcnt(4)
	v_mfma_f32_32x32x16_bf16 v[98:113], v[146:149], v[142:145], v[98:113]
	ds_read_b128 v[146:149], v209 offset:32768
	ds_read_b128 v[150:153], v209 offset:36864
	ds_read_b128 v[154:157], v209 offset:40960
	ds_read_b128 v[158:161], v209 offset:45056
	s_add_i32 s14, s77, 0xffff0000
	s_and_b32 s14, s14, 0x3e0000
	s_lshl_b32 s22, s14, 1
	s_mov_b32 m0, s70
	v_lshl_add_u64 v[164:165], v[188:189], 0, s[22:23]
	global_load_lds_dwordx4 v[164:165], off
	v_lshl_add_u64 v[164:165], v[192:193], 0, s[22:23]
	s_mov_b32 m0, s29
	s_lshl_b32 s22, s80, 1
	global_load_lds_dwordx4 v[164:165], off
	v_lshl_add_u64 v[164:165], v[190:191], 0, s[22:23]
	s_add_i32 m0, s70, 0xc000
	global_load_lds_dwordx4 v[164:165], off
	v_lshl_add_u64 v[164:165], v[194:195], 0, s[22:23]
	s_add_i32 m0, s70, 0xc400
	s_nop 0
	global_load_lds_dwordx4 v[164:165], off
	s_waitcnt lgkmcnt(4)
	v_mfma_f32_32x32x16_bf16 v[50:65], v[66:69], v[82:85], v[50:65]
	ds_read_b128 v[82:85], v210 offset:32768
	v_exp_f32_e32 v114, v114
	v_exp_f32_e32 v115, v115
	v_mfma_f32_32x32x16_bf16 v[34:49], v[66:69], v[86:89], v[34:49]
	ds_read_b128 v[86:89], v210 offset:36864
	v_exp_f32_e32 v116, v116
	v_exp_f32_e32 v117, v117
	v_mfma_f32_32x32x16_bf16 v[18:33], v[66:69], v[90:93], v[18:33]
	ds_read_b128 v[90:93], v210 offset:40960
	v_exp_f32_e32 v118, v118
	v_exp_f32_e32 v119, v119
	v_mfma_f32_32x32x16_bf16 v[2:17], v[66:69], v[94:97], v[2:17]
	ds_read_b128 v[66:69], v210 offset:45056
	v_exp_f32_e32 v120, v120
	v_exp_f32_e32 v121, v121
	s_waitcnt lgkmcnt(4)
	v_mfma_f32_32x32x16_bf16 v[50:65], v[70:73], v[146:149], v[50:65]
	ds_read_b128 v[94:97], v212 offset:32768
	v_exp_f32_e32 v122, v122
	v_exp_f32_e32 v123, v123
	v_mfma_f32_32x32x16_bf16 v[34:49], v[70:73], v[150:153], v[34:49]
	ds_read_b128 v[146:149], v212 offset:36864
	v_exp_f32_e32 v124, v124
	v_exp_f32_e32 v125, v125
	v_mfma_f32_32x32x16_bf16 v[18:33], v[70:73], v[154:157], v[18:33]
	ds_read_b128 v[150:153], v212 offset:40960
	v_exp_f32_e32 v126, v126
	v_exp_f32_e32 v127, v127
	v_mfma_f32_32x32x16_bf16 v[2:17], v[70:73], v[158:161], v[2:17]
	ds_read_b128 v[70:73], v212 offset:45056
	v_exp_f32_e32 v128, v128
	v_exp_f32_e32 v129, v129
	s_waitcnt lgkmcnt(0)
	v_mfma_f32_32x32x16_bf16 v[50:65], v[74:77], v[82:85], v[50:65]
	v_exp_f32_e32 v98, v98
	v_exp_f32_e32 v99, v99
	v_mfma_f32_32x32x16_bf16 v[34:49], v[74:77], v[86:89], v[34:49]
	v_exp_f32_e32 v100, v100
	v_exp_f32_e32 v101, v101
	v_mfma_f32_32x32x16_bf16 v[18:33], v[74:77], v[90:93], v[18:33]
	v_exp_f32_e32 v102, v102
	v_exp_f32_e32 v103, v103
	v_mfma_f32_32x32x16_bf16 v[2:17], v[74:77], v[66:69], v[2:17]
	v_exp_f32_e32 v104, v104
	v_exp_f32_e32 v105, v105
	v_mfma_f32_32x32x16_bf16 v[50:65], v[78:81], v[94:97], v[50:65]
	v_exp_f32_e32 v106, v106
	v_exp_f32_e32 v107, v107
	v_mfma_f32_32x32x16_bf16 v[34:49], v[78:81], v[146:149], v[34:49]
	v_exp_f32_e32 v108, v108
	v_exp_f32_e32 v109, v109
	v_mfma_f32_32x32x16_bf16 v[18:33], v[78:81], v[150:153], v[18:33]
	v_exp_f32_e32 v110, v110
	v_exp_f32_e32 v111, v111
	v_mfma_f32_32x32x16_bf16 v[2:17], v[78:81], v[70:73], v[2:17]
	v_exp_f32_e32 v112, v112
	v_exp_f32_e32 v113, v113
	s_and_b64 s[0:1], s[0:1], exec
	s_waitcnt vmcnt(0)
	s_cselect_b32 s14, 1, 2
	s_and_b64 s[0:1], s[40:41], exec
	s_cselect_b32 s14, s14, 0
	s_cmp_eq_u32 s14, s79
	s_waitcnt vmcnt(0)
	s_barrier
	s_cbranch_scc1 .LBB0_290
	s_cmp_eq_u32 s79, 0
	s_cselect_b64 vcc, -1, 0
	s_cmp_eq_u32 s79, 2
	s_cselect_b64 s[0:1], -1, 0
	v_cndmask_b32_e64 v66, 0, v201, s[0:1]
	s_cmp_eq_u32 s14, 2
	v_cndmask_b32_e32 v66, v66, v200, vcc
	s_cselect_b64 vcc, -1, 0
	v_cndmask_b32_e32 v67, 0, v201, vcc
	v_cndmask_b32_e64 v67, v200, v67, s[40:41]
	v_sub_f32_e32 v66, v66, v67
	v_exp_f32_e32 v66, v66
	s_nop 0
	v_pk_mul_f32 v[64:65], v[66:67], v[64:65] op_sel_hi:[0,1]
	v_pk_mul_f32 v[62:63], v[66:67], v[62:63] op_sel_hi:[0,1]
	v_pk_mul_f32 v[60:61], v[66:67], v[60:61] op_sel_hi:[0,1]
	v_pk_mul_f32 v[58:59], v[66:67], v[58:59] op_sel_hi:[0,1]
	v_pk_mul_f32 v[56:57], v[66:67], v[56:57] op_sel_hi:[0,1]
	v_pk_mul_f32 v[54:55], v[66:67], v[54:55] op_sel_hi:[0,1]
	v_pk_mul_f32 v[52:53], v[66:67], v[52:53] op_sel_hi:[0,1]
	v_pk_mul_f32 v[50:51], v[66:67], v[50:51] op_sel_hi:[0,1]
	v_pk_mul_f32 v[48:49], v[66:67], v[48:49] op_sel_hi:[0,1]
	v_pk_mul_f32 v[46:47], v[66:67], v[46:47] op_sel_hi:[0,1]
	v_pk_mul_f32 v[44:45], v[66:67], v[44:45] op_sel_hi:[0,1]
	v_pk_mul_f32 v[42:43], v[66:67], v[42:43] op_sel_hi:[0,1]
	v_pk_mul_f32 v[40:41], v[66:67], v[40:41] op_sel_hi:[0,1]
	v_pk_mul_f32 v[38:39], v[66:67], v[38:39] op_sel_hi:[0,1]
	v_pk_mul_f32 v[36:37], v[66:67], v[36:37] op_sel_hi:[0,1]
	v_pk_mul_f32 v[34:35], v[66:67], v[34:35] op_sel_hi:[0,1]
	v_pk_mul_f32 v[32:33], v[66:67], v[32:33] op_sel_hi:[0,1]
	v_pk_mul_f32 v[30:31], v[66:67], v[30:31] op_sel_hi:[0,1]
	v_pk_mul_f32 v[28:29], v[66:67], v[28:29] op_sel_hi:[0,1]
	v_pk_mul_f32 v[26:27], v[66:67], v[26:27] op_sel_hi:[0,1]
	v_pk_mul_f32 v[24:25], v[66:67], v[24:25] op_sel_hi:[0,1]
	v_pk_mul_f32 v[22:23], v[66:67], v[22:23] op_sel_hi:[0,1]
	v_pk_mul_f32 v[20:21], v[66:67], v[20:21] op_sel_hi:[0,1]
	v_pk_mul_f32 v[18:19], v[66:67], v[18:19] op_sel_hi:[0,1]
	v_pk_mul_f32 v[16:17], v[66:67], v[16:17] op_sel_hi:[0,1]
	v_pk_mul_f32 v[14:15], v[66:67], v[14:15] op_sel_hi:[0,1]
	v_pk_mul_f32 v[12:13], v[66:67], v[12:13] op_sel_hi:[0,1]
	v_pk_mul_f32 v[10:11], v[66:67], v[10:11] op_sel_hi:[0,1]
	v_pk_mul_f32 v[8:9], v[66:67], v[8:9] op_sel_hi:[0,1]
	v_pk_mul_f32 v[6:7], v[66:67], v[6:7] op_sel_hi:[0,1]
	v_pk_mul_f32 v[4:5], v[66:67], v[4:5] op_sel_hi:[0,1]
	v_pk_mul_f32 v[2:3], v[66:67], v[2:3] op_sel_hi:[0,1]
	v_mul_f32_e32 v0, v0, v66
	s_branch .LBB0_291

.LBB0_291:
	ds_read_b128 v[174:177], v202
	ds_read_b128 v[170:173], v202 offset:8192
	ds_read_b128 v[166:169], v204
	ds_read_b128 v[162:165], v204 offset:8192
	ds_read_b128 v[158:161], v205
	ds_read_b128 v[154:157], v205 offset:8192
	ds_read_b128 v[150:153], v206
	ds_read_b128 v[146:149], v206 offset:8192
	v_pk_add_f32 v[66:67], v[114:115], v[98:99]
	v_pk_add_f32 v[68:69], v[116:117], v[100:101]
	v_pk_add_f32 v[70:71], v[118:119], v[102:103]
	v_pk_add_f32 v[72:73], v[120:121], v[104:105]
	v_pk_add_f32 v[74:75], v[122:123], v[106:107]
	v_pk_add_f32 v[76:77], v[124:125], v[108:109]
	v_pk_add_f32 v[78:79], v[126:127], v[110:111]
	v_pk_add_f32 v[80:81], v[128:129], v[112:113]
	v_pk_add_f32 v[66:67], v[66:67], v[68:69]
	v_pk_add_f32 v[70:71], v[70:71], v[72:73]
	v_pk_add_f32 v[74:75], v[74:75], v[76:77]
	v_pk_add_f32 v[78:79], v[78:79], v[80:81]
	v_pk_add_f32 v[66:67], v[66:67], v[70:71]
	v_pk_add_f32 v[74:75], v[74:75], v[78:79]
	v_cvt_pk_bf16_f32 v113, v112, v113
	v_cvt_pk_bf16_f32 v112, v110, v111
	v_cvt_pk_bf16_f32 v111, v108, v109
	v_cvt_pk_bf16_f32 v110, v106, v107
	v_pk_add_f32 v[66:67], v[66:67], v[74:75]
	v_cvt_pk_bf16_f32 v109, v104, v105
	v_cvt_pk_bf16_f32 v108, v102, v103
	v_cvt_pk_bf16_f32 v107, v100, v101
	v_cvt_pk_bf16_f32 v106, v98, v99
	v_cvt_pk_bf16_f32 v98, v114, v115
	v_cvt_pk_bf16_f32 v99, v116, v117
	v_cvt_pk_bf16_f32 v100, v118, v119
	v_cvt_pk_bf16_f32 v101, v120, v121
	v_cvt_pk_bf16_f32 v102, v122, v123
	v_cvt_pk_bf16_f32 v103, v124, v125
	v_cvt_pk_bf16_f32 v104, v126, v127
	v_cvt_pk_bf16_f32 v105, v128, v129
	v_add_f32_e32 v82, v66, v67
	s_nop 0
	v_add_f32_e32 v213, v82, v0
	ds_read_b128 v[114:117], v208 offset:49152
	ds_read_b128 v[118:121], v208 offset:53248
	ds_read_b128 v[122:125], v208 offset:57344
	ds_read_b128 v[126:129], v208 offset:61440
	s_addk_i32 s78, 0x80
	s_and_b32 s15, s78, 0xf80
	s_or_b32 s0, s15, 63
	s_cmp_gt_i32 s0, s74
	s_cselect_b64 s[0:1], -1, 0
	s_cmp_lt_i32 s15, s75
	s_cselect_b64 s[40:41], -1, 0
	s_and_b64 s[0:1], s[0:1], s[40:41]
	s_andn2_b64 vcc, exec, s[0:1]
	s_mov_b64 s[0:1], -1
	s_cbranch_vccz .LBB0_293
	s_waitcnt lgkmcnt(11)
	v_mfma_f32_32x32x16_bf16 v[66:81], v[174:177], v[130:133], 0
	s_mov_b64 s[0:1], 0
	s_waitcnt lgkmcnt(10)
	v_mfma_f32_32x32x16_bf16 v[82:97], v[170:173], v[130:133], 0
